# scan2 batch tail rewritten (LDS reads hoisted, MFMAs back to back) + combine late loads hoisted
# speedup vs baseline: 1.0010x; 1.0010x over previous
; __device__ __forceinline__ void seq_pos(int t, int& pos, int& len) { if (t < TP) { pos = t & 2047; len = 2048; } else { pos = (t - TP) & 4095; len = 4096; } }
; __device__ __forceinline__ void ld8nt(const bf16_t* p, float (&o)[8]) { const u32x4 w = __builtin_nontemporal_load((const u32x4*)p); o[0] = bflo(w.x); o[1] = bfhi(w.x); o[2] = bflo(w.y); o[3] = bfhi(w.y); o[4] = bflo(w.z); o[5] = bfhi(w.z); o[6] = bflo(w.w); o[7] = bfhi(w.w); }
; __device__ __forceinline__ void combine_phase(KA a, int G, const int tid, const int bid) {
;     ...
;         int pos, len; seq_pos(t, pos, len); const bool first = pos == 0, last = pos == len - 1;
;         const bf16_t* P = PROJ + (size_t)t * PROJ_LD;
;         float r[8], k[8], v[8], af[8], ab[8], yf[8], yb[8], g[8];
;         shift8(P, c0, first, last, mpr, mnr, r); shift8(P, 512 + c0, first, last, mpk, mnk, k); shift8(P, 1024 + c0, first, last, mpv, mnv, v);
;         ld8nt(LO + (size_t)t * 2048 + 1024 + c0, af); ld8nt(LO + (size_t)t * 2048 + 1536 + c0, ab);
;         ld8nt(YF + (size_t)t * 512 + c0, yf); ld8nt(YB + (size_t)t * 512 + c0, yb); ld8nt(GB + (size_t)t * 512 + c0, g);
;         float bon = 0.f, sy = 0.f;
; #pragma unroll
;         for (int j = 0; j < 8; ++j) { bon += r[j] * k[j] * (2.0f + (af[j] + ab[j] - 2.0f) * kav[j]) * rkv[j]; yf[j] += yb[j]; sy += yf[j]; }
;     ...
;         ld8nt(MIX + (size_t)t * 1024 + 512 + c0, of); ld8nt(P + 1952 + 1040 + c0, gg);
.LBB0_144:
	v_cmp_gt_i32_e32 vcc, s83, v16
	v_mov_b32_e32 v115, v19
	s_nop 0
	v_cndmask_b32_e32 v17, v170, v171, vcc
	v_and_b32_e32 v102, v17, v16
	v_cmp_eq_u32_e64 s[2:3], 0, v102
	v_cmp_eq_u32_e32 vcc, v102, v17
	v_mov_b64_e32 v[102:103], s[10:11]
	v_mad_i64_i32 v[102:103], s[6:7], v16, s85, v[102:103]
	v_lshl_add_u64 v[104:105], v[102:103], 0, v[18:19]
	v_cndmask_b32_e64 v103, -1, 0, s[2:3]
	v_cndmask_b32_e64 v102, v172, 0, s[2:3]
	v_lshl_add_u64 v[102:103], v[104:105], 0, v[102:103]
	global_load_dwordx4 v[106:109], v[104:105], off
	global_load_dwordx4 v[110:113], v[102:103], off
	v_cndmask_b32_e64 v114, v173, 0, vcc
	v_ashrrev_i32_e32 v17, 31, v16
	v_lshl_add_u64 v[144:145], v[104:105], 0, v[114:115]
	global_load_dwordx4 v[114:117], v[144:145], off
	global_load_dwordx4 v[118:121], v[104:105], off offset:1024
	global_load_dwordx4 v[122:125], v[102:103], off offset:1024
	global_load_dwordx4 v[126:129], v[144:145], off offset:1024
	global_load_dwordx4 v[136:139], v[104:105], off offset:2048
	global_load_dwordx4 v[140:143], v[102:103], off offset:2048
	s_nop 0
	global_load_dwordx4 v[144:147], v[144:145], off offset:2048
	v_lshlrev_b64 v[102:103], 12, v[16:17]
	v_lshl_add_u64 v[102:103], v[98:99], 0, v[102:103]
	global_load_dwordx4 v[148:151], v[102:103], off offset:2048 nt
	global_load_dwordx4 v[152:155], v[102:103], off offset:3072 nt
	v_lshlrev_b64 v[102:103], 10, v[16:17]
	v_lshl_add_u64 v[156:157], v[92:93], 0, v[102:103]
	v_lshl_add_u64 v[182:183], v[94:95], 0, v[102:103]
	global_load_dwordx4 v[156:159], v[156:157], off nt
	v_lshl_add_u64 v[102:103], v[96:97], 0, v[102:103]
	global_load_dwordx4 v[182:185], v[182:183], off nt
	s_waitcnt vmcnt(10)
	v_and_b32_e32 v192, 0xffff0000, v114
	global_load_dwordx4 v[186:189], v[102:103], off nt
	v_lshlrev_b64 v[206:207], 11, v[16:17]
	v_mov_b32_e32 v208, 0x1000
	v_mov_b32_e32 v209, v19
	v_lshl_add_u64 v[206:207], v[100:101], 0, v[206:207]
	v_lshl_add_u64 v[208:209], v[104:105], 0, v[208:209]
	global_load_dwordx4 v[210:213], v[206:207], off offset:1024 nt
	global_load_dwordx4 v[214:217], v[208:209], off offset:1888 nt
	v_and_b32_e32 v103, 0xffff0000, v106
	v_lshlrev_b32_e32 v102, 16, v106
	v_and_b32_e32 v106, 0xffff0000, v110
	v_lshlrev_b32_e32 v110, 16, v110
	v_lshlrev_b32_e32 v114, 16, v114
	v_cndmask_b32_e64 v191, v106, 0, s[2:3]
	v_cndmask_b32_e64 v190, v110, 0, s[2:3]
	v_cndmask_b32_e64 v193, v192, 0, vcc
	v_cndmask_b32_e64 v192, v114, 0, vcc
	v_pk_add_f32 v[190:191], v[190:191], v[102:103] neg_lo:[0,1] neg_hi:[0,1]
	s_waitcnt vmcnt(11)
	v_and_b32_e32 v106, 0xffff0000, v122
	v_pk_fma_f32 v[190:191], v[80:81], v[190:191], v[102:103]
	v_pk_add_f32 v[102:103], v[192:193], v[102:103] neg_lo:[0,1] neg_hi:[0,1]
	v_lshlrev_b32_e32 v110, 16, v122
	v_pk_fma_f32 v[102:103], v[76:77], v[102:103], v[190:191]
	v_and_b32_e32 v191, 0xffff0000, v118
	v_lshlrev_b32_e32 v190, 16, v118
	s_waitcnt vmcnt(10)
	v_and_b32_e32 v114, 0xffff0000, v126
	v_lshlrev_b32_e32 v118, 16, v126
	v_cndmask_b32_e64 v193, v106, 0, s[2:3]
	v_cndmask_b32_e64 v192, v110, 0, s[2:3]
	v_cndmask_b32_e64 v195, v114, 0, vcc
	v_cndmask_b32_e64 v194, v118, 0, vcc
	v_pk_add_f32 v[192:193], v[192:193], v[190:191] neg_lo:[0,1] neg_hi:[0,1]
	v_and_b32_e32 v106, 0xffff0000, v111
	v_pk_fma_f32 v[192:193], v[64:65], v[192:193], v[190:191]
	v_pk_add_f32 v[190:191], v[194:195], v[190:191] neg_lo:[0,1] neg_hi:[0,1]
	s_waitcnt vmcnt(5)
	v_and_b32_e32 v195, 0xffff0000, v152
	v_pk_fma_f32 v[190:191], v[60:61], v[190:191], v[192:193]
	v_and_b32_e32 v193, 0xffff0000, v148
	v_lshlrev_b32_e32 v192, 16, v148
	v_lshlrev_b32_e32 v194, 16, v152
	v_pk_mul_f32 v[102:103], v[102:103], v[190:191]
	v_pk_add_f32 v[190:191], v[192:193], v[194:195]
	v_lshlrev_b32_e32 v110, 16, v111
	v_pk_add_f32 v[190:191], v[190:191], -2.0 op_sel_hi:[1,0]
	v_and_b32_e32 v111, 0xffff0000, v115
	v_pk_fma_f32 v[190:191], v[32:33], v[190:191], 2.0 op_sel_hi:[1,1,0]
	v_lshlrev_b32_e32 v114, 16, v115
	v_pk_mul_f32 v[102:103], v[102:103], v[190:191]
	v_cndmask_b32_e64 v111, v111, 0, vcc
	v_pk_mul_f32 v[102:103], v[28:29], v[102:103]
	v_and_b32_e32 v115, 0xffff0000, v127
	v_add_f32_e32 v102, 0, v102
	v_add_f32_e32 v118, v103, v102
	v_and_b32_e32 v103, 0xffff0000, v107
	v_lshlrev_b32_e32 v102, 16, v107
	v_cndmask_b32_e64 v107, v106, 0, s[2:3]
	v_cndmask_b32_e64 v106, v110, 0, s[2:3]
	v_cndmask_b32_e64 v110, v114, 0, vcc
	v_pk_add_f32 v[106:107], v[106:107], v[102:103] neg_lo:[0,1] neg_hi:[0,1]
	v_lshlrev_b32_e32 v114, 16, v123
	v_pk_fma_f32 v[106:107], v[82:83], v[106:107], v[102:103]
	v_pk_add_f32 v[102:103], v[110:111], v[102:103] neg_lo:[0,1] neg_hi:[0,1]
	v_and_b32_e32 v110, 0xffff0000, v123
	v_pk_fma_f32 v[102:103], v[78:79], v[102:103], v[106:107]
	v_and_b32_e32 v107, 0xffff0000, v119
	v_lshlrev_b32_e32 v106, 16, v119
	v_lshlrev_b32_e32 v119, 16, v127
	v_cndmask_b32_e64 v111, v110, 0, s[2:3]
	v_cndmask_b32_e64 v110, v114, 0, s[2:3]
	v_cndmask_b32_e64 v115, v115, 0, vcc
	v_cndmask_b32_e64 v114, v119, 0, vcc
	v_pk_add_f32 v[110:111], v[110:111], v[106:107] neg_lo:[0,1] neg_hi:[0,1]
	v_and_b32_e32 v119, 0xffff0000, v145
	v_pk_fma_f32 v[110:111], v[66:67], v[110:111], v[106:107]
	v_pk_add_f32 v[106:107], v[114:115], v[106:107] neg_lo:[0,1] neg_hi:[0,1]
	v_and_b32_e32 v115, 0xffff0000, v153
	v_pk_fma_f32 v[106:107], v[62:63], v[106:107], v[110:111]
	v_and_b32_e32 v111, 0xffff0000, v149
	v_lshlrev_b32_e32 v110, 16, v149
	v_lshlrev_b32_e32 v114, 16, v153
	v_pk_mul_f32 v[102:103], v[102:103], v[106:107]
	v_pk_add_f32 v[106:107], v[110:111], v[114:115]
	v_and_b32_e32 v110, 0xffff0000, v116
	v_pk_add_f32 v[106:107], v[106:107], -2.0 op_sel_hi:[1,0]
	v_cndmask_b32_e64 v111, v110, 0, vcc
; __device__ __forceinline__ void ld8nt(const bf16_t* p, float (&o)[8]) { const u32x4 w = __builtin_nontemporal_load((const u32x4*)p); o[0] = bflo(w.x); o[1] = bfhi(w.x); o[2] = bflo(w.y); o[3] = bfhi(w.y); o[4] = bflo(w.z); o[5] = bfhi(w.z); o[6] = bflo(w.w); o[7] = bfhi(w.w); }
; __device__ __forceinline__ void combine_phase(KA a, int G, const int tid, const int bid) {
;     ...
;         shift8(P, c0, first, last, mpr, mnr, r); shift8(P, 512 + c0, first, last, mpk, mnk, k); shift8(P, 1024 + c0, first, last, mpv, mnv, v);
;         ld8nt(LO + (size_t)t * 2048 + 1024 + c0, af); ld8nt(LO + (size_t)t * 2048 + 1536 + c0, ab);
;         ld8nt(YF + (size_t)t * 512 + c0, yf); ld8nt(YB + (size_t)t * 512 + c0, yb); ld8nt(GB + (size_t)t * 512 + c0, g);
;         float bon = 0.f, sy = 0.f;
; #pragma unroll
;         for (int j = 0; j < 8; ++j) { bon += r[j] * k[j] * (2.0f + (af[j] + ab[j] - 2.0f) * kav[j]) * rkv[j]; yf[j] += yb[j]; sy += yf[j]; }
;         bon += __shfl_xor(bon, 1); sy += __shfl_xor(sy, 1); bon += __shfl_xor(bon, 2); sy += __shfl_xor(sy, 2); bon += __shfl_xor(bon, 4); sy += __shfl_xor(sy, 4);
	v_pk_fma_f32 v[106:107], v[34:35], v[106:107], 2.0 op_sel_hi:[1,1,0]
	v_lshlrev_b32_e32 v114, 16, v128
	v_pk_mul_f32 v[102:103], v[102:103], v[106:107]
	v_and_b32_e32 v106, 0xffff0000, v112
	v_pk_mul_f32 v[102:103], v[30:31], v[102:103]
	v_cndmask_b32_e64 v107, v106, 0, s[2:3]
	v_add_f32_e32 v102, v102, v118
	v_add_f32_e32 v118, v103, v102
	v_and_b32_e32 v103, 0xffff0000, v108
	v_lshlrev_b32_e32 v102, 16, v108
	v_lshlrev_b32_e32 v108, 16, v112
	v_lshlrev_b32_e32 v112, 16, v116
	v_cndmask_b32_e64 v106, v108, 0, s[2:3]
	v_cndmask_b32_e64 v110, v112, 0, vcc
	v_pk_add_f32 v[106:107], v[106:107], v[102:103] neg_lo:[0,1] neg_hi:[0,1]
	v_and_b32_e32 v108, 0xffff0000, v124
	v_pk_fma_f32 v[106:107], v[88:89], v[106:107], v[102:103]
	v_pk_add_f32 v[102:103], v[110:111], v[102:103] neg_lo:[0,1] neg_hi:[0,1]
	v_lshlrev_b32_e32 v110, 16, v124
	v_pk_fma_f32 v[102:103], v[84:85], v[102:103], v[106:107]
	v_and_b32_e32 v107, 0xffff0000, v120
	v_lshlrev_b32_e32 v106, 16, v120
	v_and_b32_e32 v112, 0xffff0000, v128
	v_cndmask_b32_e64 v111, v108, 0, s[2:3]
	v_cndmask_b32_e64 v110, v110, 0, s[2:3]
	v_cndmask_b32_e64 v115, v112, 0, vcc
	v_cndmask_b32_e64 v114, v114, 0, vcc
	v_pk_add_f32 v[110:111], v[110:111], v[106:107] neg_lo:[0,1] neg_hi:[0,1]
	v_lshlrev_b32_e32 v108, 16, v113
	v_pk_fma_f32 v[110:111], v[72:73], v[110:111], v[106:107]
	v_pk_add_f32 v[106:107], v[114:115], v[106:107] neg_lo:[0,1] neg_hi:[0,1]
	v_and_b32_e32 v115, 0xffff0000, v154
	v_pk_fma_f32 v[106:107], v[68:69], v[106:107], v[110:111]
	v_and_b32_e32 v111, 0xffff0000, v150
	v_lshlrev_b32_e32 v110, 16, v150
	v_lshlrev_b32_e32 v114, 16, v154
	v_pk_mul_f32 v[102:103], v[102:103], v[106:107]
	v_pk_add_f32 v[106:107], v[110:111], v[114:115]
	v_lshlrev_b32_e32 v110, 16, v117
	v_pk_add_f32 v[106:107], v[106:107], -2.0 op_sel_hi:[1,0]
	v_and_b32_e32 v111, 0xffff0000, v129
	v_pk_fma_f32 v[106:107], v[40:41], v[106:107], 2.0 op_sel_hi:[1,1,0]
	v_cndmask_b32_e64 v111, v111, 0, vcc
	v_pk_mul_f32 v[102:103], v[102:103], v[106:107]
	v_and_b32_e32 v106, 0xffff0000, v113
	v_pk_mul_f32 v[102:103], v[36:37], v[102:103]
	v_cndmask_b32_e64 v107, v106, 0, s[2:3]
	v_add_f32_e32 v102, v102, v118
	v_add_f32_e32 v112, v103, v102
	v_and_b32_e32 v103, 0xffff0000, v109
	v_lshlrev_b32_e32 v102, 16, v109
	v_and_b32_e32 v109, 0xffff0000, v117
	v_cndmask_b32_e64 v106, v108, 0, s[2:3]
	v_cndmask_b32_e64 v109, v109, 0, vcc
	v_cndmask_b32_e64 v108, v110, 0, vcc
	v_pk_add_f32 v[106:107], v[106:107], v[102:103] neg_lo:[0,1] neg_hi:[0,1]
	v_lshlrev_b32_e32 v110, 16, v125
	v_pk_fma_f32 v[106:107], v[90:91], v[106:107], v[102:103]
	v_pk_add_f32 v[102:103], v[108:109], v[102:103] neg_lo:[0,1] neg_hi:[0,1]
	v_and_b32_e32 v108, 0xffff0000, v125
	v_pk_fma_f32 v[102:103], v[86:87], v[102:103], v[106:107]
	v_and_b32_e32 v107, 0xffff0000, v121
	v_lshlrev_b32_e32 v106, 16, v121
	v_lshlrev_b32_e32 v113, 16, v129
	v_cndmask_b32_e64 v109, v108, 0, s[2:3]
	v_cndmask_b32_e64 v108, v110, 0, s[2:3]
	v_cndmask_b32_e64 v110, v113, 0, vcc
	v_pk_add_f32 v[108:109], v[108:109], v[106:107] neg_lo:[0,1] neg_hi:[0,1]
	s_waitcnt vmcnt(3)
	v_and_b32_e32 v113, 0xffff0000, v185
	v_pk_fma_f32 v[108:109], v[74:75], v[108:109], v[106:107]
	v_pk_add_f32 v[106:107], v[110:111], v[106:107] neg_lo:[0,1] neg_hi:[0,1]
	v_and_b32_e32 v111, 0xffff0000, v155
	v_pk_fma_f32 v[106:107], v[70:71], v[106:107], v[108:109]
	v_and_b32_e32 v109, 0xffff0000, v151
	v_lshlrev_b32_e32 v108, 16, v151
	v_lshlrev_b32_e32 v110, 16, v155
	v_pk_mul_f32 v[102:103], v[102:103], v[106:107]
	v_pk_add_f32 v[106:107], v[108:109], v[110:111]
	v_and_b32_e32 v108, 0xffff0000, v143
	v_pk_add_f32 v[106:107], v[106:107], -2.0 op_sel_hi:[1,0]
	v_lshlrev_b32_e32 v110, 16, v147
	v_pk_fma_f32 v[106:107], v[42:43], v[106:107], 2.0 op_sel_hi:[1,1,0]
	v_and_b32_e32 v111, 0xffff0000, v147
	v_pk_mul_f32 v[102:103], v[102:103], v[106:107]
	v_lshlrev_b32_e32 v106, 16, v139
	v_pk_mul_f32 v[102:103], v[38:39], v[102:103]
	v_and_b32_e32 v107, 0xffff0000, v139
	v_add_f32_e32 v102, v102, v112
	v_add_f32_e32 v102, v103, v102
	ds_bpermute_b32 v103, v130, v102
	v_cndmask_b32_e64 v109, v108, 0, s[2:3]
	v_cndmask_b32_e64 v111, v111, 0, vcc
	v_cndmask_b32_e64 v110, v110, 0, vcc
	v_lshlrev_b32_e32 v112, 16, v185
	s_waitcnt lgkmcnt(0)
	v_add_f32_e32 v102, v102, v103
	ds_bpermute_b32 v103, v131, v102
	v_lshlrev_b32_e32 v114, 16, v146
	v_and_b32_e32 v115, 0xffff0000, v146
	v_cndmask_b32_e64 v115, v115, 0, vcc
	v_cndmask_b32_e64 v114, v114, 0, vcc
	s_waitcnt lgkmcnt(0)
	v_add_f32_e32 v102, v102, v103
	ds_bpermute_b32 v103, v133, v102
	v_lshlrev_b32_e32 v116, 16, v184
	v_and_b32_e32 v117, 0xffff0000, v184
	v_lshlrev_b32_e32 v118, 16, v145
	v_cndmask_b32_e64 v119, v119, 0, vcc
	s_waitcnt lgkmcnt(0)
; __device__ __forceinline__ void ld8nt(const bf16_t* p, float (&o)[8]) { const u32x4 w = __builtin_nontemporal_load((const u32x4*)p); o[0] = bflo(w.x); o[1] = bfhi(w.x); o[2] = bflo(w.y); o[3] = bfhi(w.y); o[4] = bflo(w.z); o[5] = bfhi(w.z); o[6] = bflo(w.w); o[7] = bfhi(w.w); }
; __device__ __forceinline__ void combine_phase(KA a, int G, const int tid, const int bid) {
;     ...
;         ld8nt(YF + (size_t)t * 512 + c0, yf); ld8nt(YB + (size_t)t * 512 + c0, yb); ld8nt(GB + (size_t)t * 512 + c0, g);
;         float bon = 0.f, sy = 0.f;
; #pragma unroll
;         for (int j = 0; j < 8; ++j) { bon += r[j] * k[j] * (2.0f + (af[j] + ab[j] - 2.0f) * kav[j]) * rkv[j]; yf[j] += yb[j]; sy += yf[j]; }
;         bon += __shfl_xor(bon, 1); sy += __shfl_xor(sy, 1); bon += __shfl_xor(bon, 2); sy += __shfl_xor(sy, 2); bon += __shfl_xor(bon, 4); sy += __shfl_xor(sy, 4);
;         const float mean = sy * (1.0f / 64.0f);
;         float sv = 0.f;
; #pragma unroll
;         for (int j = 0; j < 8; ++j) { yf[j] -= mean; sv += yf[j] * yf[j]; }
;         sv += __shfl_xor(sv, 1); sv += __shfl_xor(sv, 2); sv += __shfl_xor(sv, 4);
;         const float rstd = __builtin_amdgcn_rsqf(sv * (1.0f / 64.0f) + 64e-5f);
	v_add_f32_e32 v102, v102, v103
	v_lshlrev_b32_e32 v103, 16, v143
	v_cndmask_b32_e64 v108, v103, 0, s[2:3]
	v_pk_add_f32 v[108:109], v[108:109], v[106:107] neg_lo:[0,1] neg_hi:[0,1]
	v_lshlrev_b32_e32 v103, 16, v142
	v_pk_fma_f32 v[108:109], v[58:59], v[108:109], v[106:107]
	v_pk_add_f32 v[106:107], v[110:111], v[106:107] neg_lo:[0,1] neg_hi:[0,1]
	v_lshlrev_b32_e32 v110, 16, v159
	v_and_b32_e32 v111, 0xffff0000, v159
	v_pk_add_f32 v[122:123], v[110:111], v[112:113]
	v_and_b32_e32 v112, 0xffff0000, v142
	v_lshlrev_b32_e32 v110, 16, v138
	v_and_b32_e32 v111, 0xffff0000, v138
	v_cndmask_b32_e64 v113, v112, 0, s[2:3]
	v_cndmask_b32_e64 v112, v103, 0, s[2:3]
	v_pk_add_f32 v[112:113], v[112:113], v[110:111] neg_lo:[0,1] neg_hi:[0,1]
	v_lshlrev_b32_e32 v103, 16, v141
	v_pk_fma_f32 v[112:113], v[56:57], v[112:113], v[110:111]
	v_pk_add_f32 v[110:111], v[114:115], v[110:111] neg_lo:[0,1] neg_hi:[0,1]
	v_lshlrev_b32_e32 v114, 16, v158
	v_and_b32_e32 v115, 0xffff0000, v158
	v_pk_add_f32 v[124:125], v[114:115], v[116:117]
	v_and_b32_e32 v116, 0xffff0000, v141
	v_lshlrev_b32_e32 v114, 16, v137
	v_and_b32_e32 v115, 0xffff0000, v137
	v_cndmask_b32_e64 v117, v116, 0, s[2:3]
	v_cndmask_b32_e64 v116, v103, 0, s[2:3]
	v_cndmask_b32_e64 v118, v118, 0, vcc
	v_pk_add_f32 v[116:117], v[116:117], v[114:115] neg_lo:[0,1] neg_hi:[0,1]
	v_lshlrev_b32_e32 v120, 16, v183
	v_pk_fma_f32 v[116:117], v[54:55], v[116:117], v[114:115]
	v_pk_add_f32 v[114:115], v[118:119], v[114:115] neg_lo:[0,1] neg_hi:[0,1]
	v_lshlrev_b32_e32 v118, 16, v157
	v_and_b32_e32 v119, 0xffff0000, v157
	v_and_b32_e32 v121, 0xffff0000, v183
	v_pk_add_f32 v[126:127], v[118:119], v[120:121]
	v_lshlrev_b32_e32 v103, 16, v140
	v_and_b32_e32 v120, 0xffff0000, v140
	v_lshlrev_b32_e32 v118, 16, v136
	v_and_b32_e32 v119, 0xffff0000, v136
	v_lshlrev_b32_e32 v128, 16, v144
	v_and_b32_e32 v129, 0xffff0000, v144
	v_cndmask_b32_e64 v121, v120, 0, s[2:3]
	v_cndmask_b32_e64 v120, v103, 0, s[2:3]
	v_cndmask_b32_e64 v129, v129, 0, vcc
	v_cndmask_b32_e64 v128, v128, 0, vcc
	v_pk_add_f32 v[120:121], v[120:121], v[118:119] neg_lo:[0,1] neg_hi:[0,1]
	v_lshlrev_b32_e32 v136, 16, v182
	v_pk_fma_f32 v[120:121], v[52:53], v[120:121], v[118:119]
	v_pk_add_f32 v[118:119], v[128:129], v[118:119] neg_lo:[0,1] neg_hi:[0,1]
	v_lshlrev_b32_e32 v128, 16, v156
	v_and_b32_e32 v129, 0xffff0000, v156
	v_and_b32_e32 v137, 0xffff0000, v182
	v_pk_add_f32 v[128:129], v[128:129], v[136:137]
	v_pk_fma_f32 v[118:119], v[44:45], v[118:119], v[120:121]
	v_add_f32_e32 v103, 0, v128
	v_add_f32_e32 v103, v129, v103
	v_add_f32_e32 v103, v126, v103
	v_add_f32_e32 v103, v127, v103
	v_add_f32_e32 v103, v124, v103
	v_add_f32_e32 v103, v125, v103
	v_add_f32_e32 v103, v122, v103
	v_add_f32_e32 v103, v123, v103
	ds_bpermute_b32 v136, v130, v103
	s_waitcnt vmcnt(2)
	v_lshlrev_b32_e32 v120, 16, v186
	v_and_b32_e32 v121, 0xffff0000, v186
	v_pk_fma_f32 v[114:115], v[46:47], v[114:115], v[116:117]
	v_lshlrev_b32_e32 v116, 16, v187
	s_waitcnt lgkmcnt(0)
	v_add_f32_e32 v103, v103, v136
	ds_bpermute_b32 v136, v131, v103
	v_and_b32_e32 v117, 0xffff0000, v187
	v_pk_fma_f32 v[110:111], v[48:49], v[110:111], v[112:113]
	v_lshlrev_b32_e32 v112, 16, v188
	v_and_b32_e32 v113, 0xffff0000, v188
	s_waitcnt lgkmcnt(0)
	v_add_f32_e32 v103, v103, v136
	ds_bpermute_b32 v136, v133, v103
	v_pk_fma_f32 v[106:107], v[50:51], v[106:107], v[108:109]
	v_lshlrev_b32_e32 v108, 16, v189
	v_and_b32_e32 v109, 0xffff0000, v189
	v_add_co_u32_e32 v104, vcc, s25, v104
	s_waitcnt lgkmcnt(0)
	v_add_f32_e32 v103, v103, v136
	v_mul_f32_e32 v136, 0x3c800000, v103
	v_pk_add_f32 v[128:129], v[128:129], v[136:137] op_sel_hi:[1,0] neg_lo:[0,1] neg_hi:[0,1]
	v_pk_add_f32 v[126:127], v[126:127], v[136:137] op_sel_hi:[1,0] neg_lo:[0,1] neg_hi:[0,1]
	v_pk_mul_f32 v[138:139], v[128:129], v[128:129]
	v_pk_mul_f32 v[140:141], v[126:127], v[126:127]
	v_add_f32_e32 v103, v138, v139
	v_pk_add_f32 v[124:125], v[124:125], v[136:137] op_sel_hi:[1,0] neg_lo:[0,1] neg_hi:[0,1]
	v_add_f32_e32 v103, v140, v103
	v_pk_mul_f32 v[142:143], v[124:125], v[124:125]
	v_add_f32_e32 v103, v141, v103
	v_pk_add_f32 v[122:123], v[122:123], v[136:137] op_sel_hi:[1,0] neg_lo:[0,1] neg_hi:[0,1]
	v_add_f32_e32 v103, v142, v103
	v_pk_mul_f32 v[136:137], v[122:123], v[122:123]
	v_add_f32_e32 v103, v143, v103
	v_add_f32_e32 v103, v136, v103
	v_add_f32_e32 v103, v137, v103
	ds_bpermute_b32 v136, v130, v103
	v_addc_co_u32_e32 v105, vcc, 0, v105, vcc
	s_waitcnt lgkmcnt(0)
	v_add_f32_e32 v103, v103, v136
	ds_bpermute_b32 v136, v131, v103
	s_waitcnt lgkmcnt(0)
	v_add_f32_e32 v103, v103, v136
	ds_bpermute_b32 v136, v133, v103
	s_waitcnt lgkmcnt(0)
; __device__ __forceinline__ float sigmoidf_(float z) { return __builtin_amdgcn_rcpf(1.0f + __expf(-z)); }
; __device__ __forceinline__ void ld8nt(const bf16_t* p, float (&o)[8]) { const u32x4 w = __builtin_nontemporal_load((const u32x4*)p); o[0] = bflo(w.x); o[1] = bfhi(w.x); o[2] = bflo(w.y); o[3] = bfhi(w.y); o[4] = bflo(w.z); o[5] = bfhi(w.z); o[6] = bflo(w.w); o[7] = bfhi(w.w); }
; __device__ __forceinline__ u32x4 st8(const float (&v)[8]) { u32x4 w; w.x = pk2(v[0], v[1]); w.y = pk2(v[2], v[3]); w.z = pk2(v[4], v[5]); w.w = pk2(v[6], v[7]); return w; }
; __device__ __forceinline__ void combine_phase(KA a, int G, const int tid, const int bid) {
;     ...
;         const float rstd = __builtin_amdgcn_rsqf(sv * (1.0f / 64.0f) + 64e-5f);
;         float o[8];
; #pragma unroll
;         for (int j = 0; j < 8; ++j) o[j] = (yf[j] * rstd * lw[j] + lb[j] + bon * v[j]) * g[j];
;         *(u32x4*)(MIX + (size_t)t * 1024 + c0) = st8(o);
;         float of[8], gg[8];
;         ld8nt(MIX + (size_t)t * 1024 + 512 + c0, of); ld8nt(P + 1952 + 1040 + c0, gg);
;         float ss = 0.f;
; #pragma unroll
;         for (int j = 0; j < 8; ++j) ss += of[j] * of[j];
;         ss += __shfl_xor(ss, 1); ss += __shfl_xor(ss, 2); ss += __shfl_xor(ss, 4); ss += __shfl_xor(ss, 8);
;         const float rsg = __builtin_amdgcn_rsqf(ss * (1.0f / 128.0f) + 1e-5f);
; #pragma unroll
;         for (int j = 0; j < 8; ++j) o[j] = of[j] * rsg * gnw[j] * gg[j] * sigmoidf_(gg[j]);
;         *(u32x4*)(MIX + (size_t)t * 1024 + 512 + c0) = st8(o);
	v_add_f32_e32 v103, v103, v136
	v_mov_b32_e32 v136, 0x3a27c5ac
	v_fmamk_f32 v103, v103, 0x3c800000, v136
	v_rsq_f32_e32 v136, v103
	s_nop 0
	v_pk_mul_f32 v[128:129], v[128:129], v[136:137] op_sel_hi:[1,0]
	s_nop 0
	v_pk_fma_f32 v[128:129], v[12:13], v[128:129], v[8:9]
	s_nop 0
	v_pk_fma_f32 v[118:119], v[118:119], v[102:103], v[128:129] op_sel_hi:[1,0,1]
	s_nop 0
	v_pk_mul_f32 v[118:119], v[118:119], v[120:121]
	v_pk_mul_f32 v[120:121], v[126:127], v[136:137] op_sel_hi:[1,0]
	s_nop 0
	v_pk_fma_f32 v[120:121], v[14:15], v[120:121], v[10:11]
	s_nop 0
	v_pk_fma_f32 v[114:115], v[114:115], v[102:103], v[120:121] op_sel_hi:[1,0,1]
	s_nop 0
	v_pk_mul_f32 v[114:115], v[114:115], v[116:117]
	v_pk_mul_f32 v[116:117], v[124:125], v[136:137] op_sel_hi:[1,0]
	s_nop 0
	v_pk_fma_f32 v[116:117], v[24:25], v[116:117], v[20:21]
	s_nop 0
	v_pk_fma_f32 v[110:111], v[110:111], v[102:103], v[116:117] op_sel_hi:[1,0,1]
	s_nop 0
	v_pk_mul_f32 v[110:111], v[110:111], v[112:113]
	v_pk_mul_f32 v[112:113], v[122:123], v[136:137] op_sel_hi:[1,0]
	s_nop 0
	v_pk_fma_f32 v[112:113], v[26:27], v[112:113], v[22:23]
	s_nop 0
	v_pk_fma_f32 v[102:103], v[106:107], v[102:103], v[112:113] op_sel_hi:[1,0,1]
	v_cvt_pk_bf16_f32 v106, v118, v119
	v_pk_mul_f32 v[102:103], v[102:103], v[108:109]
	v_cvt_pk_bf16_f32 v107, v114, v115
	v_cvt_pk_bf16_f32 v109, v102, v103
	v_lshlrev_b64 v[102:103], 11, v[16:17]
	v_cvt_pk_bf16_f32 v108, v110, v111
	v_lshl_add_u64 v[102:103], v[100:101], 0, v[102:103]
	global_store_dwordx4 v[102:103], v[106:109], off
	v_add_u32_e32 v16, s14, v16
	v_cmp_lt_i32_e32 vcc, s81, v16
	s_or_b64 s[4:5], vcc, s[4:5]
	s_waitcnt vmcnt(1)
	v_mov_b32_e32 v120, v210
	v_mov_b32_e32 v121, v211
	v_mov_b32_e32 v122, v212
	v_mov_b32_e32 v123, v213
	v_mov_b32_e32 v124, v214
	v_mov_b32_e32 v125, v215
	v_mov_b32_e32 v126, v216
	v_mov_b32_e32 v127, v217
	v_lshlrev_b32_e32 v106, 16, v123
	v_lshlrev_b32_e32 v108, 16, v126
	v_mul_f32_e32 v17, 0xbfb8aa3b, v108
	v_exp_f32_e32 v17, v17
	v_and_b32_e32 v109, 0xffff0000, v126
	v_lshlrev_b32_e32 v114, 16, v125
	v_and_b32_e32 v115, 0xffff0000, v125
	v_add_f32_e32 v17, 1.0, v17
	v_rcp_f32_e32 v112, v17
	v_mul_f32_e32 v17, 0xbfb8aa3b, v109
	v_exp_f32_e32 v17, v17
	v_and_b32_e32 v107, 0xffff0000, v123
	v_lshlrev_b32_e32 v110, 16, v122
	v_and_b32_e32 v111, 0xffff0000, v122
	v_add_f32_e32 v17, 1.0, v17
	v_rcp_f32_e32 v113, v17
	v_mul_f32_e32 v17, 0xbfb8aa3b, v114
	v_exp_f32_e32 v17, v17
	v_lshlrev_b32_e32 v122, 16, v120
	v_and_b32_e32 v123, 0xffff0000, v120
	v_lshlrev_b32_e32 v120, 16, v124
	v_add_f32_e32 v17, 1.0, v17
	v_rcp_f32_e32 v118, v17
	v_mul_f32_e32 v17, 0xbfb8aa3b, v115
	v_exp_f32_e32 v17, v17
	v_lshlrev_b32_e32 v116, 16, v121
	v_and_b32_e32 v117, 0xffff0000, v121
	v_and_b32_e32 v121, 0xffff0000, v124
	v_add_f32_e32 v17, 1.0, v17
	v_rcp_f32_e32 v119, v17
	v_mul_f32_e32 v17, 0xbfb8aa3b, v120
	v_exp_f32_e32 v17, v17
	v_pk_mul_f32 v[138:139], v[122:123], v[122:123]
	v_pk_mul_f32 v[136:137], v[116:117], v[116:117]
	v_lshlrev_b32_e32 v104, 16, v127
	v_add_f32_e32 v17, 1.0, v17
	v_rcp_f32_e32 v124, v17
	v_mul_f32_e32 v17, 0xbfb8aa3b, v121
	v_exp_f32_e32 v17, v17
	v_and_b32_e32 v105, 0xffff0000, v127
	v_pk_mul_f32 v[126:127], v[110:111], v[110:111]
	v_pk_mul_f32 v[128:129], v[106:107], v[106:107]
	v_add_f32_e32 v17, 1.0, v17
	v_rcp_f32_e32 v125, v17
	v_add_f32_e32 v17, v138, v139
	v_add_f32_e32 v17, v136, v17
	v_add_f32_e32 v17, v137, v17
	v_add_f32_e32 v17, v126, v17
	v_add_f32_e32 v17, v127, v17
	v_add_f32_e32 v17, v128, v17
	v_add_f32_e32 v17, v129, v17
	ds_bpermute_b32 v126, v130, v17
	s_waitcnt lgkmcnt(0)
	v_add_f32_e32 v17, v17, v126
	ds_bpermute_b32 v126, v131, v17
	s_waitcnt lgkmcnt(0)
	v_add_f32_e32 v17, v17, v126
	ds_bpermute_b32 v126, v133, v17
	s_waitcnt lgkmcnt(0)
	v_add_f32_e32 v17, v17, v126
	ds_bpermute_b32 v126, v135, v17
	s_waitcnt lgkmcnt(0)
	v_add_f32_e32 v17, v17, v126
	v_mov_b32_e32 v126, 0x3727c5ac
	v_fmamk_f32 v17, v17, 0x3c000000, v126
	v_rsq_f32_e32 v126, v17
	v_mul_f32_e32 v17, 0xbfb8aa3b, v104
	v_exp_f32_e32 v17, v17
	v_pk_mul_f32 v[110:111], v[126:127], v[110:111] op_sel_hi:[0,1]
	v_pk_mul_f32 v[110:111], v[4:5], v[110:111]
	v_add_f32_e32 v17, 1.0, v17
	v_pk_mul_f32 v[108:109], v[110:111], v[108:109]
	v_rcp_f32_e32 v110, v17
	v_mul_f32_e32 v17, 0xbfb8aa3b, v105
	v_exp_f32_e32 v17, v17
	v_pk_mul_f32 v[122:123], v[126:127], v[122:123] op_sel_hi:[0,1]
	v_pk_mul_f32 v[116:117], v[126:127], v[116:117] op_sel_hi:[0,1]
	v_pk_mul_f32 v[106:107], v[126:127], v[106:107] op_sel_hi:[0,1]
	v_add_f32_e32 v17, 1.0, v17
	v_rcp_f32_e32 v111, v17
	v_pk_mul_f32 v[122:123], v[0:1], v[122:123]
	v_pk_mul_f32 v[116:117], v[2:3], v[116:117]
	v_pk_mul_f32 v[106:107], v[6:7], v[106:107]
	v_pk_mul_f32 v[120:121], v[122:123], v[120:121]
	v_pk_mul_f32 v[114:115], v[116:117], v[114:115]
	v_pk_mul_f32 v[106:107], v[106:107], v[104:105]
	v_pk_mul_f32 v[120:121], v[124:125], v[120:121]
	v_pk_mul_f32 v[114:115], v[118:119], v[114:115]
	v_pk_mul_f32 v[108:109], v[112:113], v[108:109]
	v_pk_mul_f32 v[110:111], v[110:111], v[106:107]
	v_cvt_pk_bf16_f32 v104, v120, v121
	v_cvt_pk_bf16_f32 v105, v114, v115
	v_cvt_pk_bf16_f32 v106, v108, v109
	v_cvt_pk_bf16_f32 v107, v110, v111
	global_store_dwordx4 v[102:103], v[104:107], off offset:1024
	s_andn2_b64 exec, exec, s[4:5]
	s_cbranch_execnz .LBB0_144

; #define LAS __attribute__((address_space(3)))
; __device__ __forceinline__ void scan2_phase(KA a, LAS unsigned char* lds, int G, const int tid, const int bid) {
;     ...
;             const u32x2 z2 = (u32x2){0u, 0u};
;             bf16x8 sb[2];
; #pragma unroll
;             for (int kb = 0; kb < 2; ++kb) { u32x4 w; w.x = pk2(accS[2 * kb][0], accS[2 * kb][1]); w.y = pk2(accS[2 * kb][2], accS[2 * kb][3]); w.z = pk2(accS[2 * kb + 1][0], accS[2 * kb + 1][1]); w.w = pk2(accS[2 * kb + 1][2], accS[2 * kb + 1][3]); sb[kb] = __builtin_bit_cast(bf16x8, w); }
;             const u32x2 vlo = *(const LAS u32x2*)(VT + (16 * r + fr) * 24 + 4 * fq);
;             f32x4 accX = (f32x4){0.f, 0.f, 0.f, 0.f}, accY = (f32x4){0.f, 0.f, 0.f, 0.f};
; #pragma unroll
;             for (int kb = 0; kb < 2; ++kb) { const u32x2 lo = *(const LAS u32x2*)(At + fr * 72 + 32 * kb + 4 * fq), hi = *(const LAS u32x2*)(At + fr * 72 + 32 * kb + 16 + 4 * fq); accX = __builtin_amdgcn_mfma_f32_16x16x32_bf16(mk8(lo, hi), sb[kb], accX, 0, 0, 0); }
;             { const u32x2 alo = *(const LAS u32x2*)(MkaT + fr * 24 + 4 * fq); accX = __builtin_amdgcn_mfma_f32_16x16x32_bf16(mk8(alo, z2), mk8(vlo, z2), accX, 0, 0, 0); }
; #pragma unroll
;             for (int kb = 0; kb < 2; ++kb) { const u32x2 lo = *(const LAS u32x2*)(Rt + fr * 72 + 32 * kb + 4 * fq), hi = *(const LAS u32x2*)(Rt + fr * 72 + 32 * kb + 16 + 4 * fq); accY = __builtin_amdgcn_mfma_f32_16x16x32_bf16(mk8(lo, hi), sb[kb], accY, 0, 0, 0); }
;             {
;                 f32x4 accSA = (f32x4){0.f, 0.f, 0.f, 0.f};
; #pragma unroll
;                 for (int kk = 0; kk < 4; ++kk) accSA = __builtin_amdgcn_mfma_f32_16x16x4f32(TTf[fr * 20 + 4 * fq + kk], accX[kk], accSA, 0, 0, 0);
;                 u32x2 sav; sav.x = pk2(accSA[0], accSA[1]); sav.y = pk2(accSA[2], accSA[3]);
;                 const bf16x8 bsv = mk8(sav, vlo);
;                 { const u32x2 lo = *(const LAS u32x2*)(MbrT + fr * 24 + 4 * fq), hi = *(const LAS u32x2*)(MkrT + fr * 24 + 4 * fq); accY = __builtin_amdgcn_mfma_f32_16x16x32_bf16(mk8(lo, hi), bsv, accY, 0, 0, 0); }
; #pragma unroll
;                 for (int i = 0; i < 4; ++i) { const int tau = b * 16 + 4 * fq + i; const int t = dir ? len - 1 - tau : tau; Y[(size_t)(row0 + t) * 512 + h * 64 + 16 * r + fr] = (bf16_t)f2bf(accY[i]); }
; #pragma unroll
;                 for (int jt = 0; jt < 4; ++jt) {
.LBB0_180:
	v_lshl_add_u32 v52, v78, 1, s84
	s_waitcnt lgkmcnt(0)
	s_barrier
	v_add_u32_e32 v44, v52, v135
	v_add_u32_e32 v16, v52, v91
	ds_read2_b64 v[32:35], v44 offset1:4
	ds_read2_b64 v[36:39], v44 offset0:8 offset1:12
	v_add_u32_e32 v53, v44, v115
	ds_read_b64 v[28:29], v16 offset:15360
	ds_read_b64 v[198:199], v53 offset:18432
	v_add_u32_e32 v40, 0x800, v44
	ds_read2_b64 v[60:63], v40 offset0:32 offset1:36
	ds_read2_b64 v[64:67], v40 offset0:40 offset1:44
	v_lshlrev_b32_e32 v18, 2, v78
	v_add3_u32 v18, s84, v93, v18
	ds_read_b128 v[56:59], v18 offset:22016
	ds_read_b64 v[202:203], v53 offset:19200
	ds_read_b64 v[204:205], v53 offset:19968
	ds_read_b64 v[208:209], v16 offset:15360
	v_cvt_pk_bf16_f32 v20, v12, v13
	v_cvt_pk_bf16_f32 v21, v14, v15
	v_cvt_pk_bf16_f32 v22, v0, v1
	v_cvt_pk_bf16_f32 v23, v2, v3
	v_cvt_pk_bf16_f32 v24, v4, v5
	v_cvt_pk_bf16_f32 v25, v6, v7
	v_cvt_pk_bf16_f32 v26, v8, v9
	v_cvt_pk_bf16_f32 v27, v10, v11
	v_mov_b32_e32 v30, v19
	v_mov_b32_e32 v31, v19
	v_mov_b32_e32 v200, v19
	v_mov_b32_e32 v201, v19
	v_lshl_add_u32 v17, v92, 1, v52
	s_waitcnt lgkmcnt(9)
	v_mfma_f32_16x16x32_bf16 v[32:35], v[32:35], v[20:23], 0
	s_waitcnt lgkmcnt(8)
	v_mfma_f32_16x16x32_bf16 v[32:35], v[36:39], v[24:27], v[32:35]
	s_waitcnt lgkmcnt(5)
	v_mfma_f32_16x16x32_bf16 v[68:71], v[60:63], v[20:23], 0
	v_mfma_f32_16x16x32_bf16 v[32:35], v[198:201], v[28:31], v[32:35]
	s_waitcnt lgkmcnt(4)
	v_mfma_f32_16x16x32_bf16 v[68:71], v[64:67], v[24:27], v[68:71]
	s_waitcnt lgkmcnt(0)
	ds_read_b64 v[210:211], v17 offset:9216
	ds_read_b64 v[212:213], v17 offset:12288
	ds_read_b64 v[214:215], v17 offset:9984
	ds_read_b64 v[216:217], v17 offset:13056
	ds_read_b64 v[218:219], v17 offset:10752
	ds_read_b64 v[220:221], v17 offset:13824
	ds_read_b64 v[222:223], v17 offset:11520
	ds_read_b64 v[224:225], v17 offset:14592
	v_add_u32_e32 v16, v52, v79
	ds_read_b128 v[182:185], v16 offset:23296
	ds_read_b128 v[186:189], v16 offset:23360
	ds_read_b128 v[190:193], v16 offset:23424
	ds_read_b128 v[194:197], v16 offset:23488
	v_mfma_f32_16x16x4_f32 v[72:75], v56, v32, 0
	v_mfma_f32_16x16x4_f32 v[72:75], v57, v33, v[72:75]
	v_mfma_f32_16x16x4_f32 v[72:75], v58, v34, v[72:75]
	v_mfma_f32_16x16x4_f32 v[72:75], v59, v35, v[72:75]
	v_add_u32_e32 v18, s81, v78
	v_add_u32_e32 v16, s77, v143
	v_cndmask_b32_e64 v16, v16, v18, s[8:9]
	v_add_u32_e32 v16, s76, v16
	v_ashrrev_i32_e32 v17, 31, v16
	v_lshlrev_b64 v[16:17], 10, v[16:17]
	v_lshl_add_u64 v[16:17], v[86:87], 0, v[16:17]
	v_mov_b32_e32 v226, 0xfffffc00
	v_mov_b32_e32 v227, 0x400
	v_cndmask_b32_e64 v226, v226, v227, s[8:9]
	v_ashrrev_i32_e32 v227, 31, v226
	s_nop 3
	v_cvt_pk_bf16_f32 v206, v72, v73
	v_cvt_pk_bf16_f32 v207, v74, v75
	s_nop 1
	v_mfma_f32_16x16x32_bf16 v[68:71], v[202:205], v[206:209], v[68:71]
	s_waitcnt lgkmcnt(10)
	v_mfma_f32_16x16x32_bf16 v[12:15], v[210:213], v[206:209], v[12:15]
	s_waitcnt lgkmcnt(8)
	v_mfma_f32_16x16x32_bf16 v[0:3], v[214:217], v[206:209], v[0:3]
	s_waitcnt lgkmcnt(6)
	v_mfma_f32_16x16x32_bf16 v[4:7], v[218:221], v[206:209], v[4:7]
	s_waitcnt lgkmcnt(4)
	v_mfma_f32_16x16x32_bf16 v[8:11], v[222:225], v[206:209], v[8:11]
	s_nop 1
	v_cvt_pk_bf16_f32 v24, v68, s0
	global_store_short v[16:17], v24, off
	v_lshl_add_u64 v[16:17], v[16:17], 0, v[226:227]
	v_cvt_pk_bf16_f32 v25, v69, s0
	global_store_short v[16:17], v25, off
	v_lshl_add_u64 v[16:17], v[16:17], 0, v[226:227]
	v_cvt_pk_bf16_f32 v26, v70, s0
	global_store_short v[16:17], v26, off
	v_lshl_add_u64 v[16:17], v[16:17], 0, v[226:227]
	v_cvt_pk_bf16_f32 v27, v71, s0
	global_store_short v[16:17], v27, off
	s_waitcnt lgkmcnt(0)
	v_pk_mul_f32 v[12:13], v[12:13], v[182:183]
	v_pk_mul_f32 v[14:15], v[14:15], v[184:185]
	v_pk_mul_f32 v[0:1], v[0:1], v[186:187]
	v_pk_mul_f32 v[2:3], v[2:3], v[188:189]
	v_pk_mul_f32 v[4:5], v[4:5], v[190:191]
	v_pk_mul_f32 v[6:7], v[6:7], v[192:193]
	v_pk_mul_f32 v[8:9], v[8:9], v[194:195]
	v_pk_mul_f32 v[10:11], v[10:11], v[196:197]
	s_add_i32 s81, s81, 16
	s_add_i32 s30, s30, -16
	v_add_u32_e32 v143, -16, v143
	s_cmp_eq_u32 s82, s83
	s_cbranch_scc1 .LBB0_173
